# v27: v26 + attention row-max across lane groups via v_permlane16_swap/v_permlane32_swap instead of two ds_bpermute round trips (lever 7: intra-wave movement without LDS)
# speedup vs baseline: 1.0098x; 1.0016x over previous
.LBB0_325:
	v_max3_f32 v37, s41, v0, v1
	v_max3_f32 v38, v3, v32, v28
	v_max3_f32 v37, v37, v29, v30
	v_max3_f32 v38, v38, v31, v40
	v_max3_f32 v37, v37, v41, v42
	v_max3_f32 v38, v38, v43, v44
	v_max3_f32 v37, v37, v45, v46
	v_max3_f32 v38, v38, v47, v48
	v_max3_f32 v37, v37, v49, v50
	v_max3_f32 v38, v38, v51, v52
	v_max3_f32 v37, v37, v53, v54
	v_max3_f32 v38, v38, v55, v56
	v_max3_f32 v37, v37, v57, v58
	v_max3_f32 v38, v38, v59, v60
	v_max3_f32 v37, v37, v61, v62
	v_max3_f32 v38, v38, v63, v36
	v_max3_f32 v37, v37, v33, v34
	v_max3_f32 v37, v37, v38, v35
	s_add_i32 s40, s42, s77
	s_and_b32 s40, s40, 0x80
	v_mov_b32_e32 v38, v37
	s_mov_b32 s81, s80
	s_mov_b32 s82, s80
	s_mov_b32 s83, s80
	v_permlane16_swap_b32_e32 v38, v37
	v_max_f32_e32 v37, v37, v38
	v_mov_b32_e32 v38, v37
	s_nop 1
	v_permlane32_swap_b32_e32 v38, v37
	v_max_f32_e32 v37, v37, v38
	v_sub_f32_e32 v38, v40, v37
	v_exp_f32_e32 v73, v38
	v_sub_f32_e32 v38, v41, v37
	v_exp_f32_e32 v75, v38
	v_sub_f32_e32 v38, v42, v37
	v_exp_f32_e32 v77, v38
	v_sub_f32_e32 v38, v43, v37
	v_exp_f32_e32 v123, v38
	v_sub_f32_e32 v38, v44, v37
	v_exp_f32_e32 v124, v38
	v_sub_f32_e32 v38, v45, v37
	v_exp_f32_e32 v125, v38
	v_sub_f32_e32 v38, v46, v37
	v_exp_f32_e32 v126, v38
	v_sub_f32_e32 v38, v47, v37
	v_exp_f32_e32 v127, v38
	v_sub_f32_e32 v38, v48, v37
	v_exp_f32_e32 v46, v38
	v_sub_f32_e32 v38, v49, v37
	v_sub_f32_e32 v0, v0, v37
	v_sub_f32_e32 v1, v1, v37
	v_exp_f32_e32 v47, v38
	v_sub_f32_e32 v38, v50, v37
	v_exp_f32_e32 v0, v0
	v_exp_f32_e32 v1, v1
	v_exp_f32_e32 v48, v38
	v_sub_f32_e32 v38, v51, v37
	v_exp_f32_e32 v49, v38
	v_sub_f32_e32 v38, v52, v37
	v_exp_f32_e32 v50, v38
	v_sub_f32_e32 v38, v53, v37
	v_exp_f32_e32 v51, v38
	v_sub_f32_e32 v38, v54, v37
	v_cvt_pk_bf16_f32 v54, v0, v1
	v_sub_f32_e32 v0, v32, v37
	v_sub_f32_e32 v1, v3, v37
	v_exp_f32_e32 v0, v0
	v_exp_f32_e32 v1, v1
	v_exp_f32_e32 v52, v38
	v_sub_f32_e32 v38, v55, v37
	v_exp_f32_e32 v53, v38
	v_cvt_pk_bf16_f32 v55, v0, v1
	v_sub_f32_e32 v0, v28, v37
	v_sub_f32_e32 v1, v29, v37
	v_exp_f32_e32 v0, v0
	v_exp_f32_e32 v1, v1
	v_sub_f32_e32 v38, v56, v37
	v_sub_f32_e32 v39, v57, v37
	v_sub_f32_e32 v40, v58, v37
	v_cvt_pk_bf16_f32 v56, v0, v1
	v_sub_f32_e32 v0, v30, v37
	v_sub_f32_e32 v1, v31, v37
	v_exp_f32_e32 v0, v0
	v_exp_f32_e32 v1, v1
	v_sub_f32_e32 v41, v59, v37
	v_sub_f32_e32 v42, v60, v37
	v_sub_f32_e32 v43, v61, v37
	v_cvt_pk_bf16_f32 v57, v0, v1
	s_mul_i32 s40, s40, 0x90
	v_add_u32_e32 v0, s40, v145
	s_add_i32 s40, s45, s77
	s_and_b32 s40, s40, 0x80
	s_mul_i32 s40, s40, 0x90
	v_add_u32_e32 v1, s40, v146
	ds_read_b64_tr_b16 v[30:31], v1 offset:36864
	ds_read_b64_tr_b16 v[60:61], v1 offset:36896
	ds_read_b64_tr_b16 v[28:29], v0 offset:36864
	ds_read_b64_tr_b16 v[58:59], v0 offset:36896
	s_waitcnt lgkmcnt(1)
	v_mfma_f32_16x16x32_bf16 v[110:113], v[28:31], v[54:57], 0
	ds_read_b64_tr_b16 v[28:29], v0 offset:36928
	ds_read_b64_tr_b16 v[30:31], v1 offset:36928
	s_add_i32 s40, s44, s77
	s_and_b32 s40, s40, 0x80
	s_waitcnt lgkmcnt(0)
	v_mfma_f32_16x16x32_bf16 v[114:117], v[28:31], v[54:57], 0
	ds_read_b64_tr_b16 v[28:29], v0 offset:36960
	ds_read_b64_tr_b16 v[30:31], v1 offset:36960
	s_mul_i32 s40, s40, 0x90
	v_add_u32_e32 v0, s40, v147
	s_add_i32 s40, s99, s77
	s_and_b32 s40, s40, 0x80
	s_mul_i32 s40, s40, 0x90
	v_add_u32_e32 v1, s40, v148
	v_cvt_pk_bf16_f32 v124, v124, v125
	v_cvt_pk_bf16_f32 v125, v126, v127
	ds_read_b64_tr_b16 v[128:129], v1 offset:36864
	ds_read_b64_tr_b16 v[132:133], v1 offset:36896
	ds_read_b64_tr_b16 v[126:127], v0 offset:36864
	ds_read_b64_tr_b16 v[130:131], v0 offset:36896
	v_cvt_pk_bf16_f32 v122, v73, v75
	v_cvt_pk_bf16_f32 v123, v77, v123
	s_waitcnt lgkmcnt(4)
	v_mfma_f32_16x16x32_bf16 v[118:121], v[28:31], v[54:57], 0
	v_mov_b64_e32 v[28:29], s[80:81]
	v_mov_b64_e32 v[30:31], s[82:83]
	s_add_i32 s40, s98, s77
	s_waitcnt lgkmcnt(1)
	v_mfma_f32_16x16x32_bf16 v[110:113], v[126:129], v[122:125], v[110:113]
	ds_read_b64_tr_b16 v[126:127], v0 offset:36928
	ds_read_b64_tr_b16 v[128:129], v1 offset:36928
	s_and_b32 s40, s40, 0x80
	v_cvt_pk_bf16_f32 v46, v46, v47
	s_waitcnt lgkmcnt(0)
	v_mfma_f32_16x16x32_bf16 v[114:117], v[126:129], v[122:125], v[114:117]
	ds_read_b64_tr_b16 v[126:127], v0 offset:36960
	ds_read_b64_tr_b16 v[128:129], v1 offset:36960
	s_mul_i32 s40, s40, 0x90
	v_add_u32_e32 v0, s40, v149
	s_add_i32 s40, s97, s77
	v_mfma_f32_16x16x32_bf16 v[58:61], v[58:61], v[54:57], 0
	s_and_b32 s40, s40, 0x80
	s_mul_i32 s40, s40, 0x90
	v_add_u32_e32 v1, s40, v150
	v_mfma_f32_16x16x32_bf16 v[54:57], v[28:31], v[54:57], 0
	v_cvt_pk_bf16_f32 v47, v48, v49
	v_cvt_pk_bf16_f32 v48, v50, v51
	v_cvt_pk_bf16_f32 v49, v52, v53
	v_mfma_f32_16x16x32_bf16 v[58:61], v[130:133], v[122:125], v[58:61]
	s_add_i32 s40, s96, s77
	v_sub_f32_e32 v44, v62, v37
	s_waitcnt lgkmcnt(0)
	v_mfma_f32_16x16x32_bf16 v[118:121], v[126:129], v[122:125], v[118:121]
	v_sub_f32_e32 v45, v63, v37
	s_and_b32 s40, s40, 0x80
	v_exp_f32_e32 v38, v38
	v_mfma_f32_16x16x32_bf16 v[54:57], v[28:31], v[122:125], v[54:57]
	ds_read_b64_tr_b16 v[52:53], v1 offset:36864
	ds_read_b64_tr_b16 v[124:125], v1 offset:36896
	ds_read_b64_tr_b16 v[50:51], v0 offset:36864
	ds_read_b64_tr_b16 v[122:123], v0 offset:36896
	v_exp_f32_e32 v39, v39
	v_exp_f32_e32 v40, v40
	s_waitcnt lgkmcnt(1)
	v_mfma_f32_16x16x32_bf16 v[50:53], v[50:53], v[46:49], v[110:113]
	s_nop 2
	ds_read_b64_tr_b16 v[110:111], v0 offset:36928
	ds_read_b64_tr_b16 v[112:113], v1 offset:36928
	v_exp_f32_e32 v41, v41
	v_exp_f32_e32 v42, v42
	s_waitcnt lgkmcnt(0)
	v_mfma_f32_16x16x32_bf16 v[110:113], v[110:113], v[46:49], v[114:117]
	s_nop 2
	ds_read_b64_tr_b16 v[114:115], v0 offset:36960
	ds_read_b64_tr_b16 v[116:117], v1 offset:36960
	v_exp_f32_e32 v43, v43
	v_exp_f32_e32 v44, v44
	v_exp_f32_e32 v45, v45
	s_mul_i32 s40, s40, 0x90
	v_add_u32_e32 v0, s40, v151
	s_add_i32 s40, s94, s77
	s_and_b32 s40, s40, 0x80
	s_mul_i32 s40, s40, 0x90
	v_add_u32_e32 v1, s40, v152
	v_mfma_f32_16x16x32_bf16 v[58:61], v[122:125], v[46:49], v[58:61]
	v_cvt_pk_bf16_f32 v38, v38, v39
	v_cvt_pk_bf16_f32 v39, v40, v41
	v_cvt_pk_bf16_f32 v40, v42, v43
	s_waitcnt lgkmcnt(0)
	v_mfma_f32_16x16x32_bf16 v[114:117], v[114:117], v[46:49], v[118:121]
	v_cvt_pk_bf16_f32 v41, v44, v45
	v_sub_f32_e32 v36, v36, v37
	v_mfma_f32_16x16x32_bf16 v[46:49], v[28:31], v[46:49], v[54:57]
	ds_read_b64_tr_b16 v[44:45], v1 offset:36864
	s_nop 1
	ds_read_b64_tr_b16 v[56:57], v1 offset:36896
	ds_read_b64_tr_b16 v[42:43], v0 offset:36864
	ds_read_b64_tr_b16 v[54:55], v0 offset:36896
	v_sub_f32_e32 v33, v33, v37
	v_exp_f32_e32 v36, v36
	v_exp_f32_e32 v33, v33
	s_add_i32 s40, s93, s77
	v_sub_f32_e32 v34, v34, v37
	v_sub_f32_e32 v35, v35, v37
	s_waitcnt lgkmcnt(1)
	v_mfma_f32_16x16x32_bf16 v[42:45], v[42:45], v[38:41], v[50:53]
	s_and_b32 s40, s40, 0x80
	v_exp_f32_e32 v34, v34
	v_exp_f32_e32 v35, v35
	s_waitcnt lgkmcnt(0)
	v_mfma_f32_16x16x32_bf16 v[50:53], v[54:57], v[38:41], v[58:61]
	ds_read_b64_tr_b16 v[54:55], v0 offset:36928
	ds_read_b64_tr_b16 v[56:57], v1 offset:36928
	s_nop 0
	ds_read_b64_tr_b16 v[58:59], v0 offset:36960
	ds_read_b64_tr_b16 v[60:61], v1 offset:36960
	v_or_b32_e32 v32, s40, v105
	s_add_i32 s40, s92, s77
	s_and_b32 s40, s40, 0x80
	v_cvt_pk_bf16_f32 v0, v36, v33
	v_or_b32_e32 v33, s40, v106
	v_mad_u32_u24 v62, v33, s33, v108
	s_waitcnt lgkmcnt(2)
	v_mfma_f32_16x16x32_bf16 v[54:57], v[54:57], v[38:41], v[110:113]
	v_cvt_pk_bf16_f32 v1, v34, v35
	v_mad_u32_u24 v36, v32, s33, v108
	v_mov_b32_e32 v3, v2
	s_waitcnt lgkmcnt(0)
	v_mfma_f32_16x16x32_bf16 v[58:61], v[58:61], v[38:41], v[114:117]
	v_mfma_f32_16x16x32_bf16 v[38:41], v[28:31], v[38:41], v[46:49]
	ds_read_b64_tr_b16 v[34:35], v62 offset:36864
	s_nop 1
	ds_read_b64_tr_b16 v[48:49], v62 offset:36896
	ds_read_b64_tr_b16 v[32:33], v36 offset:36864
	ds_read_b64_tr_b16 v[46:47], v36 offset:36896
	s_waitcnt lgkmcnt(1)
	v_mfma_f32_16x16x32_bf16 v[32:35], v[32:35], v[0:3], v[42:45]
	s_waitcnt lgkmcnt(0)
	v_mfma_f32_16x16x32_bf16 v[42:45], v[46:49], v[0:3], v[50:53]
	ds_read_b64_tr_b16 v[46:47], v36 offset:36928
	ds_read_b64_tr_b16 v[48:49], v62 offset:36928
	s_nop 0
	ds_read_b64_tr_b16 v[50:51], v36 offset:36960
	ds_read_b64_tr_b16 v[52:53], v62 offset:36960
	v_mfma_f32_16x16x32_bf16 v[28:31], v[28:31], v[0:3], v[38:41]
	s_waitcnt lgkmcnt(2)
	v_mfma_f32_16x16x32_bf16 v[46:49], v[46:49], v[0:3], v[54:57]
	s_waitcnt lgkmcnt(0)
	v_mfma_f32_16x16x32_bf16 v[50:53], v[50:53], v[0:3], v[58:61]
	s_nop 3
	v_div_scale_f32 v0, s[40:41], v28, v28, 1.0
	v_rcp_f32_e32 v1, v0
	s_nop 0
	v_fma_f32 v3, -v0, v1, 1.0
	v_fmac_f32_e32 v1, v3, v1
	v_div_scale_f32 v3, vcc, 1.0, v28, 1.0
	v_mul_f32_e32 v29, v3, v1
	v_fma_f32 v30, -v0, v29, v3
	v_fmac_f32_e32 v29, v30, v1
	v_fma_f32 v0, -v0, v29, v3
	v_div_fmas_f32 v0, v0, v1, v29
	v_div_fixup_f32 v0, v0, v28, 1.0
	v_pk_mul_f32 v[34:35], v[34:35], v[0:1] op_sel_hi:[1,0]
	v_pk_mul_f32 v[32:33], v[32:33], v[0:1] op_sel_hi:[1,0]
	v_lshl_add_u64 v[30:31], v[84:85], 0, s[46:47]
	v_cvt_pk_bf16_f32 v32, v32, v33
	v_cvt_pk_bf16_f32 v33, v34, v35
	global_store_dwordx2 v[30:31], v[32:33], off offset:-64
	v_pk_mul_f32 v[32:33], v[44:45], v[0:1] op_sel_hi:[1,0]
	v_pk_mul_f32 v[34:35], v[42:43], v[0:1] op_sel_hi:[1,0]
	s_nop 0
	v_cvt_pk_bf16_f32 v34, v34, v35
	v_cvt_pk_bf16_f32 v35, v32, v33
	global_store_dwordx2 v[30:31], v[34:35], off offset:-32
	v_pk_mul_f32 v[32:33], v[48:49], v[0:1] op_sel_hi:[1,0]
	v_pk_mul_f32 v[34:35], v[46:47], v[0:1] op_sel_hi:[1,0]
	s_nop 0
	v_cvt_pk_bf16_f32 v34, v34, v35
	v_cvt_pk_bf16_f32 v35, v32, v33
	v_pk_mul_f32 v[32:33], v[52:53], v[0:1] op_sel_hi:[1,0]
	v_pk_mul_f32 v[0:1], v[50:51], v[0:1] op_sel_hi:[1,0]
	global_store_dwordx2 v[30:31], v[34:35], off
	v_cvt_pk_bf16_f32 v0, v0, v1
	v_cvt_pk_bf16_f32 v1, v32, v33
	global_store_dwordx2 v[30:31], v[0:1], off offset:32
	s_and_saveexec_b64 s[48:49], s[4:5]
	s_cbranch_execz .LBB0_320
	s_mov_b32 s40, 0x800000
	v_cmp_gt_f32_e32 vcc, s40, v28
	s_mov_b32 s40, 0x3f317217
	v_add_u32_e32 v0, s77, v76
	v_cndmask_b32_e64 v1, 0, 32, vcc
	v_ldexp_f32 v1, v28, v1
	v_log_f32_e32 v3, v1
	v_lshlrev_b32_e32 v0, s76, v0
	v_add_u32_e32 v0, s75, v0
	v_ashrrev_i32_e32 v1, 31, v0
	v_mul_f32_e32 v28, 0x3f317217, v3
	v_fma_f32 v28, v3, s40, -v28
	v_fmac_f32_e32 v28, 0x3377d1cf, v3
	s_mov_b32 s40, 0x7f800000
	v_fmac_f32_e32 v28, 0x3f317217, v3
	v_cmp_lt_f32_e64 s[40:41], |v3|, s40
	v_lshlrev_b64 v[0:1], 6, v[0:1]
	v_lshl_add_u64 v[0:1], s[0:1], 0, v[0:1]
	v_cndmask_b32_e64 v3, v3, v28, s[40:41]
	v_mov_b32_e32 v28, 0x41b17218
	v_cndmask_b32_e32 v28, 0, v28, vcc
	v_sub_f32_e32 v3, v3, v28
	v_fmac_f32_e32 v3, 0x3f317218, v37
	global_store_dword v[0:1], v3, off
	s_branch .LBB0_320
